# phase_lru_scan fast path: XCD-aware unit map (the two 32-channel groups sharing each 128-byte line of g and y run on the same XCD, so the line is fetched / written back once); gates epilogue load hois
# speedup vs baseline: 1.0123x; 1.0123x over previous
; #define LAS __attribute__((address_space(3)))
; DI int otid() { int t = threadIdx.x; asm volatile("" : "+v"(t)); return t; }
; DI void phase_lru_scan(const Params& p, LAS unsigned char* lds) {
;     const unsigned* ax = (const unsigned*)(p.ws + ACT + 128 * MiB); const bf16_t* big = (const bf16_t*)(p.ws + ACT);
;     bf16_t* y = (bf16_t*)(p.ws + HBUF);
;     LAS unsigned* tile = (LAS unsigned*)lds;
;     LAS float* sP = (LAS float*)(lds + 65536); LAS float* sH = sP + 512; LAS float* sC = sH + 512;
;     const int tid = otid(), seg = tid >> 5, chl = tid & 31;
;     for (int u = blockIdx.x; u < 256; u += gridDim.x) {
;         const int b = u >> 6, ch = (u & 63) * 32 + chl;
;         const size_t rowbase = (size_t)b * SEQ;
;         unsigned pre[32];
; #pragma unroll
;         for (int i = 0; i < 32; ++i) pre[i] = ax[(rowbase + seg + 16 * i) * DM + ch];
;         __syncthreads();
;         if (tid < 32) sC[tid] = 0.f;
.LBB0_1009:
	s_or_b64 exec, exec, s[8:9]
	v_mov_b32_e32 v4, v181
	s_and_b64 vcc, exec, s[6:7]
	s_waitcnt lgkmcnt(0)
	s_barrier
	s_cbranch_vccnz .LBB0_1026
	s_cmp_eq_u32 s18, 0x100
	s_cbranch_scc0 .Llr_orig
	s_load_dwordx2 s[6:7], s[0:1], 0xf0
	v_and_b32_e32 v126, 31, v181
	v_lshrrev_b32_e32 v113, 5, v181
	v_lshlrev_b32_e32 v112, 2, v126
	v_lshl_add_u32 v114, v113, 12, v112
	v_lshlrev_b32_e32 v127, 1, v126
	v_lshl_add_u32 v115, v113, 11, v127
	v_add_u32_e32 v115, 65536, v115
	v_lshlrev_b32_e32 v116, 2, v181
	v_add_u32_e32 v116, 98304, v116
	v_add_u32_e32 v117, 98304, v112
	v_lshrrev_b32_e32 v128, 3, v181
	v_and_b32_e32 v129, 7, v181
	v_lshlrev_b32_e32 v118, 7, v128
	v_lshl_add_u32 v118, v129, 4, v118
	v_lshlrev_b32_e32 v120, 13, v128
	v_lshl_add_u32 v120, v129, 4, v120
	v_lshrrev_b32_e32 v128, 2, v181
	v_and_b32_e32 v129, 3, v181
	v_lshlrev_b32_e32 v119, 6, v128
	v_lshl_add_u32 v119, v129, 4, v119
	v_add_u32_e32 v119, 65536, v119
	v_lshlrev_b32_e32 v121, 13, v128
	v_lshl_add_u32 v121, v129, 4, v121
	v_lshlrev_b32_e32 v122, 12, v128
	v_lshl_add_u32 v122, v129, 4, v122
	s_lshr_b32 s10, s2, 3
	s_and_b32 s9, s2, 7
	s_lshr_b32 s8, s10, 3
	s_bfe_u32 s11, s10, 0x20001
	s_lshl_b32 s11, s11, 3
	s_add_u32 s9, s9, s11
	s_lshl_b32 s9, s9, 1
	s_and_b32 s10, s10, 1
	s_or_b32 s9, s9, s10
	s_lshl_b32 s10, s8, 25
	s_lshl_b32 s11, s9, 7
	s_waitcnt lgkmcnt(0)
	s_add_u32 s12, s6, 0x13f00000
	s_addc_u32 s13, s7, 0
	s_add_u32 s12, s12, s10
	s_addc_u32 s13, s13, 0
	s_add_u32 s12, s12, s11
	s_addc_u32 s13, s13, 0
	s_lshl_b32 s11, s9, 6
	s_add_u32 s14, s6, 0xbf01000
	s_addc_u32 s15, s7, 0
	s_add_u32 s14, s14, s10
	s_addc_u32 s15, s15, 0
	s_add_u32 s14, s14, s11
	s_addc_u32 s15, s15, 0
	s_lshl_b32 s10, s8, 24
	s_add_u32 s16, s6, 0x7f00000
	s_addc_u32 s17, s7, 0
	s_add_u32 s16, s16, s10
	s_addc_u32 s17, s17, 0
	s_add_u32 s16, s16, s11
	s_addc_u32 s17, s17, 0
	s_mov_b64 s[24:25], s[12:13]
	global_load_dwordx4 v[64:67], v120, s[24:25]
	s_add_u32 s24, s24, 0x80000
	s_addc_u32 s25, s25, 0
	global_load_dwordx4 v[68:71], v120, s[24:25]
	s_add_u32 s24, s24, 0x80000
	s_addc_u32 s25, s25, 0
	global_load_dwordx4 v[72:75], v120, s[24:25]
	s_add_u32 s24, s24, 0x80000
	s_addc_u32 s25, s25, 0
	global_load_dwordx4 v[76:79], v120, s[24:25]
	s_add_u32 s24, s24, 0x80000
	s_addc_u32 s25, s25, 0
	global_load_dwordx4 v[80:83], v120, s[24:25]
	s_add_u32 s24, s24, 0x80000
	s_addc_u32 s25, s25, 0
	global_load_dwordx4 v[84:87], v120, s[24:25]
	s_add_u32 s24, s24, 0x80000
	s_addc_u32 s25, s25, 0
	global_load_dwordx4 v[88:91], v120, s[24:25]
	s_add_u32 s24, s24, 0x80000
	s_addc_u32 s25, s25, 0
	global_load_dwordx4 v[92:95], v120, s[24:25]
	s_mov_b64 s[24:25], s[14:15]
	global_load_dwordx4 v[96:99], v121, s[24:25]
	s_add_u32 s24, s24, 0x100000
	s_addc_u32 s25, s25, 0
	global_load_dwordx4 v[100:103], v121, s[24:25]
	s_add_u32 s24, s24, 0x100000
	s_addc_u32 s25, s25, 0
	global_load_dwordx4 v[104:107], v121, s[24:25]
	s_add_u32 s24, s24, 0x100000
	s_addc_u32 s25, s25, 0
	global_load_dwordx4 v[108:111], v121, s[24:25]
	s_add_u32 s12, s12, 0x400000
	s_addc_u32 s13, s13, 0
	s_add_u32 s14, s14, 0x400000
	s_addc_u32 s15, s15, 0
	v_cmp_gt_u32_e32 vcc, 32, v181
	s_and_saveexec_b64 s[26:27], vcc
	v_mov_b32_e32 v126, 0
	v_add_u32_e32 v127, 102400, v112
	ds_write_b32 v127, v126
	s_mov_b64 exec, s[26:27]
	s_mov_b64 exec, -1
	s_mov_b32 s28, 0
